# HGRN scan: prefix product chain read in one batch (no serialized LDS round trips), score / output / state fragments read ahead into idle registers
# speedup vs baseline: 1.0126x; 1.0037x over previous
.LBB0_3307:
	s_or_b64 exec, exec, s[4:5]
	s_waitcnt vmcnt(15)
	v_lshlrev_b32_e32 v16, 16, v12
	v_and_b32_e32 v17, 0xffff0000, v12
	v_mul_f32_e32 v16, 0xbfb8aa3b, v16
	v_mul_f32_e32 v17, 0xbfb8aa3b, v17
	v_exp_f32_e32 v16, v16
	v_exp_f32_e32 v17, v17
	s_waitcnt vmcnt(13)
	v_lshlrev_b32_e32 v18, 16, v14
	v_and_b32_e32 v14, 0xffff0000, v14
	v_add_f32_e32 v16, 1.0, v16
	v_add_f32_e32 v17, 1.0, v17
	v_mul_f32_e32 v18, 0xbfb8aa3b, v18
	v_mul_f32_e32 v14, 0xbfb8aa3b, v14
	v_rcp_f32_e32 v16, v16
	v_rcp_f32_e32 v17, v17
	v_exp_f32_e32 v22, v18
	v_exp_f32_e32 v14, v14
	v_pk_add_f32 v[60:61], v[54:55], 1.0 op_sel_hi:[1,0] neg_lo:[1,0] neg_hi:[1,0]
	s_waitcnt vmcnt(5)
	v_lshlrev_b32_e32 v38, 16, v9
	v_pk_fma_f32 v[18:19], v[60:61], v[16:17], v[54:55]
	v_add_f32_e32 v16, 1.0, v22
	v_add_f32_e32 v14, 1.0, v14
	v_rcp_f32_e32 v22, v16
	v_rcp_f32_e32 v23, v14
	v_and_b32_e32 v9, 0xffff0000, v9
	v_mul_f32_e32 v38, 0xbfb8aa3b, v38
	v_mul_f32_e32 v9, 0xbfb8aa3b, v9
	v_pk_fma_f32 v[26:27], v[60:61], v[22:23], v[54:55]
	v_lshlrev_b32_e32 v22, 16, v20
	v_mul_f32_e32 v22, 0xbfb8aa3b, v22
	v_exp_f32_e32 v25, v22
	v_and_b32_e32 v20, 0xffff0000, v20
	v_mul_f32_e32 v20, 0xbfb8aa3b, v20
	v_exp_f32_e32 v20, v20
	v_add_f32_e32 v25, 1.0, v25
	v_rcp_f32_e32 v32, v25
	v_lshlrev_b32_e32 v25, 16, v24
	v_and_b32_e32 v24, 0xffff0000, v24
	v_mul_f32_e32 v25, 0xbfb8aa3b, v25
	v_mul_f32_e32 v24, 0xbfb8aa3b, v24
	v_exp_f32_e32 v25, v25
	v_exp_f32_e32 v24, v24
	v_add_f32_e32 v20, 1.0, v20
	v_rcp_f32_e32 v33, v20
	v_add_f32_e32 v25, 1.0, v25
	v_add_f32_e32 v24, 1.0, v24
	v_rcp_f32_e32 v62, v25
	v_rcp_f32_e32 v63, v24
	v_lshlrev_b32_e32 v24, 16, v11
	v_and_b32_e32 v25, 0xffff0000, v11
	v_lshlrev_b32_e32 v11, 16, v30
	v_and_b32_e32 v30, 0xffff0000, v30
	v_mul_f32_e32 v11, 0xbfb8aa3b, v11
	v_exp_f32_e32 v11, v11
	v_mul_f32_e32 v30, 0xbfb8aa3b, v30
	v_exp_f32_e32 v30, v30
	v_exp_f32_e32 v38, v38
	v_exp_f32_e32 v9, v9
	v_add_f32_e32 v11, 1.0, v11
	v_pk_mul_f32 v[28:29], v[18:19], v[26:27]
	v_pk_fma_f32 v[32:33], v[60:61], v[32:33], v[54:55]
	v_rcp_f32_e32 v64, v11
	v_add_f32_e32 v11, 1.0, v30
	v_pk_mul_f32 v[34:35], v[28:29], v[32:33]
	v_pk_fma_f32 v[62:63], v[60:61], v[62:63], v[54:55]
	v_rcp_f32_e32 v65, v11
	v_add_f32_e32 v38, 1.0, v38
	v_add_f32_e32 v9, 1.0, v9
	v_pk_add_f32 v[22:23], v[26:27], 1.0 op_sel_hi:[1,0] neg_lo:[1,0] neg_hi:[1,0]
	v_pk_add_f32 v[26:27], v[32:33], 1.0 op_sel_hi:[1,0] neg_lo:[1,0] neg_hi:[1,0]
	v_pk_add_f32 v[32:33], v[62:63], 1.0 op_sel_hi:[1,0] neg_lo:[1,0] neg_hi:[1,0]
	v_pk_mul_f32 v[68:69], v[34:35], v[62:63]
	v_rcp_f32_e32 v62, v38
	v_rcp_f32_e32 v63, v9
	v_lshlrev_b32_e32 v30, 16, v10
	v_and_b32_e32 v31, 0xffff0000, v10
	v_pk_fma_f32 v[10:11], v[60:61], v[64:65], v[54:55]
	s_waitcnt vmcnt(4)
	v_lshlrev_b32_e32 v66, 16, v8
	v_pk_add_f32 v[64:65], v[10:11], 1.0 op_sel_hi:[1,0] neg_lo:[1,0] neg_hi:[1,0]
	v_pk_mul_f32 v[74:75], v[68:69], v[10:11]
	v_and_b32_e32 v67, 0xffff0000, v8
	v_pk_fma_f32 v[8:9], v[60:61], v[62:63], v[54:55]
	s_waitcnt vmcnt(3)
	v_lshlrev_b32_e32 v10, 16, v7
	v_and_b32_e32 v7, 0xffff0000, v7
	v_mul_f32_e32 v10, 0xbfb8aa3b, v10
	v_mul_f32_e32 v7, 0xbfb8aa3b, v7
	v_pk_add_f32 v[72:73], v[8:9], 1.0 op_sel_hi:[1,0] neg_lo:[1,0] neg_hi:[1,0]
	v_pk_mul_f32 v[82:83], v[74:75], v[8:9]
	s_waitcnt vmcnt(1)
	v_lshlrev_b32_e32 v8, 16, v5
	v_and_b32_e32 v5, 0xffff0000, v5
	v_exp_f32_e32 v10, v10
	v_exp_f32_e32 v7, v7
	v_mul_f32_e32 v8, 0xbfb8aa3b, v8
	v_mul_f32_e32 v5, 0xbfb8aa3b, v5
	v_exp_f32_e32 v8, v8
	v_exp_f32_e32 v5, v5
	s_and_b64 s[4:5], s[46:47], exec
	s_mov_b32 s4, 0x500000
	s_cselect_b32 s4, s4, 0x4700000
	v_add_f32_e32 v10, 1.0, v10
	v_add_f32_e32 v7, 1.0, v7
	s_add_u32 s4, s90, s4
	v_rcp_f32_e32 v10, v10
	v_rcp_f32_e32 v11, v7
	v_add_f32_e32 v8, 1.0, v8
	v_add_f32_e32 v5, 1.0, v5
	s_addc_u32 s5, s91, 0
	s_lshl_b32 s54, s0, 11
	v_rcp_f32_e32 v8, v8
	v_rcp_f32_e32 v9, v5
	s_add_u32 s4, s4, s54
	s_addc_u32 s5, s5, 0
	s_add_u32 s4, s4, s50
	v_lshlrev_b32_e32 v70, 16, v6
	v_and_b32_e32 v71, 0xffff0000, v6
	v_pk_fma_f32 v[6:7], v[60:61], v[10:11], v[54:55]
	s_addc_u32 s5, s5, 0
	v_pk_mul_f32 v[84:85], v[82:83], v[6:7]
	s_waitcnt vmcnt(0)
	v_lshlrev_b32_e32 v76, 16, v4
	v_and_b32_e32 v77, 0xffff0000, v4
	v_pk_fma_f32 v[4:5], v[60:61], v[8:9], v[54:55]
	s_add_u32 s54, s4, s51
	v_pk_add_f32 v[78:79], v[4:5], 1.0 op_sel_hi:[1,0] neg_lo:[1,0] neg_hi:[1,0]
	v_pk_mul_f32 v[86:87], v[84:85], v[4:5]
	v_mov_b32_e32 v4, 0
	s_mov_b32 s66, 0
	s_addc_u32 s55, s5, 0
	v_lshlrev_b32_e32 v12, 16, v13
	v_and_b32_e32 v13, 0xffff0000, v13
	v_pk_add_f32 v[16:17], v[18:19], 1.0 op_sel_hi:[1,0] neg_lo:[1,0] neg_hi:[1,0]
	v_lshlrev_b32_e32 v14, 16, v15
	v_and_b32_e32 v15, 0xffff0000, v15
	v_lshlrev_b32_e32 v20, 16, v21
	v_and_b32_e32 v21, 0xffff0000, v21
	v_pk_add_f32 v[80:81], v[6:7], 1.0 op_sel_hi:[1,0] neg_lo:[1,0] neg_hi:[1,0]
	v_lshl_add_u64 v[62:63], v[40:41], 1, s[48:49]
	v_mov_b32_e32 v132, v121
	v_mov_b32_e32 v133, v115
	s_mov_b32 s67, 0
	v_mov_b32_e32 v5, v4
	v_mov_b32_e32 v6, v4
	v_mov_b32_e32 v7, v4
	v_mov_b32_e32 v8, v4
	v_mov_b32_e32 v9, v4
	v_mov_b32_e32 v10, v4
	v_mov_b32_e32 v11, v4
	ds_write_b64 v107, v[86:87]
	s_waitcnt lgkmcnt(0)
	s_barrier
	s_branch .Lhg_chain

.Lhg_chain:
	v_mov_b32_e32 v51, v50
	ds_read_b64 v[88:89], v116
	ds_read_b64 v[220:221], v116 offset:512
	ds_read_b64 v[222:223], v116 offset:1024
	ds_read_b64 v[224:225], v116 offset:1536
	ds_read_b64 v[226:227], v116 offset:2048
	ds_read_b64 v[228:229], v116 offset:2560
	ds_read_b64 v[230:231], v116 offset:3072
	s_waitcnt lgkmcnt(0)
	v_cndmask_b32_e64 v88, 1.0, v88, s[10:11]
	v_cndmask_b32_e64 v89, 1.0, v89, s[10:11]
	v_cndmask_b32_e64 v220, 1.0, v220, s[12:13]
	v_cndmask_b32_e64 v221, 1.0, v221, s[12:13]
	v_pk_mul_f32 v[88:89], v[88:89], v[220:221]
	v_cndmask_b32_e64 v222, 1.0, v222, s[14:15]
	v_cndmask_b32_e64 v223, 1.0, v223, s[14:15]
	v_pk_mul_f32 v[88:89], v[88:89], v[222:223]
	v_cndmask_b32_e64 v224, 1.0, v224, s[16:17]
	v_cndmask_b32_e64 v225, 1.0, v225, s[16:17]
	v_pk_mul_f32 v[88:89], v[88:89], v[224:225]
	v_cndmask_b32_e64 v226, 1.0, v226, s[18:19]
	v_cndmask_b32_e64 v227, 1.0, v227, s[18:19]
	v_pk_mul_f32 v[88:89], v[88:89], v[226:227]
	v_cndmask_b32_e64 v228, 1.0, v228, s[20:21]
	v_cndmask_b32_e64 v229, 1.0, v229, s[20:21]
	v_pk_mul_f32 v[88:89], v[88:89], v[228:229]
	v_cndmask_b32_e64 v230, 1.0, v230, s[22:23]
	v_cndmask_b32_e64 v231, 1.0, v231, s[22:23]
	v_pk_mul_f32 v[88:89], v[88:89], v[230:231]
	v_pk_mul_f32 v[86:87], v[86:87], v[88:89]
	s_and_saveexec_b64 s[4:5], s[8:9]

.LBB0_3382:
	s_or_b64 exec, exec, s[50:51]
	v_add_u32_e32 v88, v109, v110
	ds_read_b128 v[16:19], v88
	ds_read_b128 v[20:23], v88 offset:64
	ds_read_b128 v[24:27], v88 offset:128
	ds_read_b128 v[28:31], v88 offset:192
	v_add_u32_e32 v13, v110, v45
	v_add_u32_e32 v38, v110, v117
	ds_read_b128 v[182:185], v13 offset:17600
	ds_read_b128 v[80:83], v13 offset:17536
	ds_read_b128 v[84:87], v13 offset:17472
	ds_read_b128 v[138:141], v13 offset:17408
	ds_read_b128 v[166:169], v38 offset:17600
	ds_read_b128 v[170:173], v38 offset:17536
	ds_read_b128 v[174:177], v38 offset:17472
	ds_read_b128 v[178:181], v38 offset:17408
	v_mov_b32_e32 v12, 0
	v_mov_b32_e32 v32, 0
	v_mov_b32_e32 v33, 0
	v_mov_b32_e32 v34, 0
	v_mov_b32_e32 v35, 0
	s_and_saveexec_b64 s[4:5], s[24:25]
	s_cbranch_execz .LBB0_3384
	s_waitcnt lgkmcnt(4)
	v_mfma_f32_16x16x32_bf16 v[138:141], v[138:141], v[16:19], 0
	v_mfma_f32_16x16x32_bf16 v[84:87], v[84:87], v[20:23], v[138:141]
	v_mfma_f32_16x16x32_bf16 v[80:83], v[80:83], v[24:27], v[84:87]
	v_mfma_f32_16x16x32_bf16 v[32:35], v[182:185], v[28:31], v[80:83]
.LBB0_3384:
	s_or_b64 exec, exec, s[4:5]
	s_nop 6
	v_cndmask_b32_e64 v13, v32, 0, s[28:29]
	v_cndmask_b32_e64 v14, 0, v33, s[30:31]
	v_cndmask_b32_e64 v13, v13, v32, s[30:31]
	v_cndmask_b32_e64 v15, v34, 0, s[34:35]
	v_cndmask_b32_e64 v32, v35, 0, s[36:37]
	v_cvt_pk_bf16_f32 v14, v13, v14
	v_cvt_pk_bf16_f32 v15, v15, v32
	ds_write_b64 v118, v[14:15] offset:44032
	v_mov_b32_e32 v13, 0
	v_mov_b32_e32 v14, 0
	v_mov_b32_e32 v15, 0
	s_and_saveexec_b64 s[4:5], s[26:27]
	s_cbranch_execz .LBB0_3386
	s_waitcnt lgkmcnt(1)
	v_mfma_f32_16x16x32_bf16 v[16:19], v[178:181], v[16:19], 0
	v_mfma_f32_16x16x32_bf16 v[16:19], v[174:177], v[20:23], v[16:19]
	v_mfma_f32_16x16x32_bf16 v[16:19], v[170:173], v[24:27], v[16:19]
	v_mfma_f32_16x16x32_bf16 v[12:15], v[166:169], v[28:31], v[16:19]
.LBB0_3386:
	s_or_b64 exec, exec, s[4:5]
	s_waitcnt lgkmcnt(4)
	s_nop 5
	v_cndmask_b32_e64 v16, v12, 0, s[38:39]
	v_cndmask_b32_e64 v13, 0, v13, s[40:41]
	v_cndmask_b32_e64 v12, v16, v12, s[40:41]
	v_cndmask_b32_e64 v14, v14, 0, s[42:43]
	v_cndmask_b32_e64 v15, v15, 0, s[44:45]
	v_cvt_pk_bf16_f32 v12, v12, v13
	v_cvt_pk_bf16_f32 v13, v14, v15
	v_add_u32_e32 v89, v113, v110
	ds_write_b64 v118, v[12:13] offset:44064
	s_waitcnt lgkmcnt(0)
	s_barrier
	ds_read_b128 v[12:15], v89 offset:34880
	ds_read_b128 v[16:19], v89 offset:34816
	ds_read_b128 v[20:23], v128 offset:53440
	ds_read_b128 v[24:27], v128 offset:53376
	ds_read_b128 v[28:31], v128 offset:53312
	ds_read_b128 v[32:35], v128 offset:53248
	ds_read_b128 v[80:83], v129 offset:44096
	ds_read_b128 v[84:87], v129 offset:44032
	ds_read_b128 v[138:141], v130 offset:192
	ds_read_b128 v[154:157], v130 offset:128
	ds_read_b128 v[158:161], v130 offset:64
	ds_read_b128 v[162:165], v130
	ds_read_b128 v[186:189], v124 offset:34816
	ds_read_b128 v[190:193], v124 offset:34880
	ds_read_b128 v[194:197], v124 offset:37120
	ds_read_b128 v[198:201], v124 offset:37184
	ds_read_b64_tr_b16 v[202:203], v126 offset:17408
	ds_read_b64_tr_b16 v[204:205], v126 offset:18496
	ds_read_b128 v[210:213], v125
	ds_read_b64_tr_b16 v[206:207], v126 offset:26112
	ds_read_b64_tr_b16 v[208:209], v126 offset:27200
	s_waitcnt lgkmcnt(9)
	v_mfma_f32_16x16x32_bf16 v[16:19], v[16:19], v[84:87], 0
	s_cmp_lt_u32 s67, 4
	s_cselect_b64 vcc, -1, 0
	s_movk_i32 s4, 0x100
	v_mfma_f32_16x16x32_bf16 v[12:15], v[12:15], v[80:83], v[16:19]
	v_mfma_f32_16x16x32_bf16 v[12:15], v[32:35], v[162:165], v[12:15]
	s_nop 2
	v_add_u32_e32 v16, s66, v114
	v_cndmask_b32_e32 v17, v132, v133, vcc
	v_cndmask_b32_e64 v16, v17, v16, s[46:47]
	v_mfma_f32_16x16x32_bf16 v[12:15], v[28:31], v[158:161], v[12:15]
	v_add_u32_e32 v18, 0xffffff00, v16
	v_ashrrev_i32_e32 v17, 31, v16
	v_cmp_gt_i32_e32 vcc, s4, v16
	v_mfma_f32_16x16x32_bf16 v[12:15], v[24:27], v[154:157], v[12:15]
	s_add_i32 s66, s66, 64
	v_cndmask_b32_e32 v17, 0, v17, vcc
	v_cndmask_b32_e32 v16, v18, v16, vcc
	v_cndmask_b32_e64 v38, v131, 0, vcc
	v_lshl_add_u64 v[18:19], s[54:55], 0, v[38:39]
	v_lshlrev_b64 v[16:17], 11, v[16:17]
	v_mfma_f32_16x16x32_bf16 v[12:15], v[20:23], v[138:141], v[12:15]
	v_lshl_add_u64 v[138:139], v[18:19], 0, v[16:17]
	s_waitcnt lgkmcnt(3)
	v_mfma_f32_16x16x32_bf16 v[4:7], v[202:205], v[186:189], v[4:7]
	s_waitcnt lgkmcnt(0)
	v_lshl_add_u64 v[16:17], v[42:43], 1, v[138:139]
	v_mov_b32_e32 v53, v39
	v_mfma_f32_16x16x32_bf16 v[8:11], v[202:205], v[194:197], v[8:11]
	v_lshl_add_u64 v[16:17], v[16:17], 0, v[52:53]
	v_cvt_pk_bf16_f32 v12, v12, v13
	v_cvt_pk_bf16_f32 v13, v14, v15
	global_store_dwordx2 v[16:17], v[12:13], off
	s_waitcnt vmcnt(16)
	v_lshlrev_b32_e32 v13, 16, v51
	v_and_b32_e32 v14, 0xffff0000, v51
	v_mul_f32_e32 v13, 0xbfb8aa3b, v13
	v_exp_f32_e32 v15, v13
	v_mul_f32_e32 v13, 0xbfb8aa3b, v14
	v_mfma_f32_16x16x32_bf16 v[4:7], v[206:209], v[190:193], v[4:7]
	v_exp_f32_e32 v16, v13
	v_add_f32_e32 v14, 1.0, v15
	s_waitcnt vmcnt(14)
	v_and_b32_e32 v17, 0xffff0000, v66
	v_mfma_f32_16x16x32_bf16 v[8:11], v[206:209], v[198:201], v[8:11]
	v_add_f32_e32 v15, 1.0, v16
	s_nop 1
	v_pk_mul_f32 v[4:5], v[210:211], v[4:5]
	v_lshlrev_b32_e32 v16, 16, v66
	v_mul_f32_e32 v16, 0xbfb8aa3b, v16
	v_rcp_f32_e32 v14, v14
	s_nop 0
	v_pk_mul_f32 v[8:9], v[210:211], v[8:9]
	s_waitcnt vmcnt(8)
	v_lshlrev_b32_e32 v32, 16, v72
	v_and_b32_e32 v33, 0xffff0000, v72
	v_mul_f32_e32 v32, 0xbfb8aa3b, v32
	v_rcp_f32_e32 v15, v15
	v_exp_f32_e32 v16, v16
	v_mul_f32_e32 v17, 0xbfb8aa3b, v17
	v_lshlrev_b32_e32 v22, 16, v68
	v_exp_f32_e32 v38, v32
	v_mul_f32_e32 v32, 0xbfb8aa3b, v33
	v_exp_f32_e32 v17, v17
	v_and_b32_e32 v23, 0xffff0000, v68
	v_mul_f32_e32 v22, 0xbfb8aa3b, v22
	v_lshlrev_b32_e32 v26, 16, v70
	v_exp_f32_e32 v51, v32
	v_exp_f32_e32 v24, v22
	v_mul_f32_e32 v22, 0xbfb8aa3b, v23
	v_and_b32_e32 v27, 0xffff0000, v70
	v_mul_f32_e32 v26, 0xbfb8aa3b, v26
	v_exp_f32_e32 v25, v22
	v_exp_f32_e32 v30, v26
	v_mul_f32_e32 v26, 0xbfb8aa3b, v27
	v_pk_fma_f32 v[18:19], v[60:61], v[14:15], v[54:55]
	v_add_f32_e32 v14, 1.0, v16
	v_exp_f32_e32 v31, v26
	v_add_f32_e32 v38, 1.0, v38
	v_lshlrev_b32_e32 v12, 16, v64
	v_and_b32_e32 v13, 0xffff0000, v64
	v_rcp_f32_e32 v20, v14
	v_add_f32_e32 v14, 1.0, v17
	v_rcp_f32_e32 v64, v38
	v_add_f32_e32 v38, 1.0, v51
	v_rcp_f32_e32 v21, v14
	v_lshlrev_b32_e32 v14, 16, v65
	v_and_b32_e32 v15, 0xffff0000, v65
	v_rcp_f32_e32 v65, v38
	s_waitcnt vmcnt(6)
	v_lshlrev_b32_e32 v38, 16, v74
	v_add_f32_e32 v24, 1.0, v24
	v_add_f32_e32 v25, 1.0, v25
	v_and_b32_e32 v51, 0xffff0000, v74
	v_mul_f32_e32 v38, 0xbfb8aa3b, v38
	v_rcp_f32_e32 v24, v24
	v_rcp_f32_e32 v25, v25
	v_add_f32_e32 v30, 1.0, v30
	v_add_f32_e32 v31, 1.0, v31
	v_exp_f32_e32 v38, v38
	v_mul_f32_e32 v51, 0xbfb8aa3b, v51
	v_rcp_f32_e32 v30, v30
	v_rcp_f32_e32 v31, v31
	v_exp_f32_e32 v51, v51
	v_pk_fma_f32 v[20:21], v[60:61], v[20:21], v[54:55]
	v_pk_fma_f32 v[24:25], v[60:61], v[24:25], v[54:55]
	v_pk_mul_f32 v[28:29], v[18:19], v[20:21]
	v_add_f32_e32 v38, 1.0, v38
	v_pk_mul_f32 v[6:7], v[212:213], v[6:7]
	v_pk_mul_f32 v[10:11], v[212:213], v[10:11]
	v_pk_mul_f32 v[34:35], v[28:29], v[24:25]
	v_pk_fma_f32 v[30:31], v[60:61], v[30:31], v[54:55]
	v_rcp_f32_e32 v70, v38
	v_add_f32_e32 v38, 1.0, v51
	v_pk_add_f32 v[26:27], v[24:25], 1.0 op_sel_hi:[1,0] neg_lo:[1,0] neg_hi:[1,0]
	v_lshlrev_b32_e32 v24, 16, v69
	v_and_b32_e32 v25, 0xffff0000, v69
	v_pk_add_f32 v[32:33], v[30:31], 1.0 op_sel_hi:[1,0] neg_lo:[1,0] neg_hi:[1,0]
	v_pk_mul_f32 v[68:69], v[34:35], v[30:31]
	v_lshlrev_b32_e32 v30, 16, v71
	v_and_b32_e32 v31, 0xffff0000, v71
	v_rcp_f32_e32 v71, v38
	s_waitcnt vmcnt(4)
	v_lshlrev_b32_e32 v38, 16, v77
	v_and_b32_e32 v51, 0xffff0000, v77
	v_mul_f32_e32 v38, 0xbfb8aa3b, v38
	v_exp_f32_e32 v38, v38
	v_mul_f32_e32 v51, 0xbfb8aa3b, v51
	v_exp_f32_e32 v51, v51
	v_pk_add_f32 v[22:23], v[20:21], 1.0 op_sel_hi:[1,0] neg_lo:[1,0] neg_hi:[1,0]
	v_add_f32_e32 v38, 1.0, v38
	v_rcp_f32_e32 v80, v38
	v_add_f32_e32 v38, 1.0, v51
	v_rcp_f32_e32 v81, v38
	s_waitcnt vmcnt(2)
	v_lshlrev_b32_e32 v38, 16, v79
	v_and_b32_e32 v51, 0xffff0000, v79
	v_mul_f32_e32 v38, 0xbfb8aa3b, v38
	v_exp_f32_e32 v38, v38
	v_mul_f32_e32 v51, 0xbfb8aa3b, v51
	v_exp_f32_e32 v51, v51
	v_lshlrev_b32_e32 v20, 16, v67
	v_add_f32_e32 v38, 1.0, v38
	v_rcp_f32_e32 v86, v38
	v_add_f32_e32 v38, 1.0, v51
	v_rcp_f32_e32 v87, v38
	v_and_b32_e32 v21, 0xffff0000, v67
	v_pk_fma_f32 v[66:67], v[60:61], v[64:65], v[54:55]
	v_pk_fma_f32 v[70:71], v[60:61], v[70:71], v[54:55]
	v_pk_mul_f32 v[74:75], v[68:69], v[66:67]
	v_pk_add_f32 v[64:65], v[66:67], 1.0 op_sel_hi:[1,0] neg_lo:[1,0] neg_hi:[1,0]
	v_lshlrev_b32_e32 v66, 16, v73
	v_and_b32_e32 v67, 0xffff0000, v73
	v_pk_add_f32 v[72:73], v[70:71], 1.0 op_sel_hi:[1,0] neg_lo:[1,0] neg_hi:[1,0]
	v_pk_mul_f32 v[82:83], v[74:75], v[70:71]
	v_lshlrev_b32_e32 v70, 16, v76
	v_and_b32_e32 v71, 0xffff0000, v76
	v_pk_fma_f32 v[76:77], v[60:61], v[80:81], v[54:55]
	v_pk_fma_f32 v[86:87], v[60:61], v[86:87], v[54:55]
	v_pk_mul_f32 v[84:85], v[82:83], v[76:77]
	v_pk_add_f32 v[16:17], v[18:19], 1.0 op_sel_hi:[1,0] neg_lo:[1,0] neg_hi:[1,0]
	v_pk_add_f32 v[80:81], v[76:77], 1.0 op_sel_hi:[1,0] neg_lo:[1,0] neg_hi:[1,0]
	s_waitcnt vmcnt(1)
	v_lshlrev_b32_e32 v76, 16, v78
	v_and_b32_e32 v77, 0xffff0000, v78
	v_pk_add_f32 v[78:79], v[86:87], 1.0 op_sel_hi:[1,0] neg_lo:[1,0] neg_hi:[1,0]
	v_pk_mul_f32 v[86:87], v[84:85], v[86:87]
	v_subrev_u32_e32 v133, 64, v133
	s_cmpk_eq_i32 s66, 0x20c0
	v_subrev_u32_e32 v132, 64, v132
	ds_write_b64 v107, v[86:87]
	s_waitcnt lgkmcnt(0)
	s_barrier
	s_cbranch_scc0 .LBB0_3308
	v_mov_b32_e32 v51, v50
	v_mov_b64_e32 v[54:55], v[50:51]
	s_and_saveexec_b64 s[4:5], s[10:11]
	s_cbranch_execz .LBB0_3395
	ds_read_b64 v[54:55], v116
	s_or_b64 exec, exec, s[4:5]
	s_and_saveexec_b64 s[4:5], s[12:13]
	s_cbranch_execnz .LBB0_3396
